# s1 and s3 items: staging loads (12 U tiles / 8 C,B tiles) issued at item start so their latency overlaps the cumulative-decay chain; on top of coalesced-V attention with ds_read_b64_tr_b16
# speedup vs baseline: 1.0084x; 1.0078x over previous
.LBB0_140:
	s_andn2_b64 vcc, exec, s[4:5]
	s_cbranch_vccnz .LBB0_137
	v_mov_b32_e32 v102, v201
	s_ashr_i32 s8, s37, 1
	s_lshl_b32 s4, s8, 7
	v_and_b32_e32 v105, 0x7f, v102
	v_or_b32_e32 v2, s4, v105
	v_ashrrev_i32_e32 v3, 31, v2
	v_readlane_b32 s12, v253, 46
	s_and_b32 s9, s37, 1
	v_lshlrev_b64 v[82:83], 11, v[2:3]
	v_readlane_b32 s13, v253, 47
	s_lshl_b32 s6, s9, 9
	s_mov_b32 s7, s3
	v_lshl_add_u64 v[2:3], s[12:13], 0, v[82:83]
	s_lshl_b32 s24, s8, 3
	s_lshl_b32 s8, s9, 2
	v_lshl_add_u64 v[2:3], v[2:3], 0, s[6:7]
	s_or_b32 s6, s24, s8
	v_add_u32_e32 v103, 0x200, v102
	s_ashr_i32 s7, s6, 31
	s_lshl_b32 s2, s9, 8
	v_ashrrev_i32_e32 v104, 4, v102
	v_ashrrev_i32_e32 v106, 4, v103
	s_ashr_i32 s5, s4, 31
	s_lshl_b64 s[6:7], s[6:7], 15
	v_readlane_b32 s10, v254, 9
	v_lshlrev_b32_e32 v0, 2, v102
	v_and_b32_e32 v84, -8, v104
	v_and_b32_e32 v86, -8, v106
	v_readlane_b32 s11, v254, 10
	s_add_u32 s6, s10, s6
	v_and_b32_e32 v107, 0x7c, v0
	v_ashrrev_i32_e32 v88, 5, v102
	v_ashrrev_i32_e32 v90, 5, v103
	v_ashrrev_i32_e32 v85, 31, v84
	v_ashrrev_i32_e32 v87, 31, v86
	s_addc_u32 s7, s11, s7
	v_lshlrev_b32_e32 v96, 2, v107
	v_mov_b32_e32 v97, v1
	v_ashrrev_i32_e32 v89, 31, v88
	v_ashrrev_i32_e32 v91, 31, v90
	v_ashrrev_i32_e32 v100, 6, v102
	v_and_b32_e32 v101, 15, v102
	s_waitcnt lgkmcnt(0)
	s_barrier
	v_lshl_add_u64 v[4:5], v[84:85], 1, v[2:3]
	v_lshl_add_u64 v[2:3], v[86:87], 1, v[2:3]
	v_lshl_add_u64 v[20:21], s[6:7], 0, v[96:97]
	v_lshlrev_b64 v[110:111], 9, v[88:89]
	v_lshlrev_b64 v[112:113], 9, v[90:91]
	v_lshl_or_b32 v80, v100, 4, v101
	global_load_dwordx4 v[4:7], v[4:5], off
	s_nop 0
	global_load_dwordx4 v[8:11], v[2:3], off
	v_lshl_add_u64 v[2:3], v[20:21], 0, v[110:111]
	v_lshl_add_u64 v[16:17], v[20:21], 0, v[112:113]
	v_readlane_b32 s6, v254, 1
	v_ashrrev_i32_e32 v81, 31, v80
	global_load_dwordx4 v[12:15], v[2:3], off
	s_nop 0
	global_load_dwordx4 v[16:19], v[16:17], off
	v_add_u32_e32 v2, 0x400, v102
	v_add_u32_e32 v91, 0x600, v102
	v_bfe_u32 v89, v102, 4, 2
	v_readlane_b32 s7, v254, 2
	v_ashrrev_i32_e32 v92, 5, v2
	v_ashrrev_i32_e32 v94, 5, v91
	v_lshl_add_u64 v[98:99], v[80:81], 0, s[4:5]
	v_lshlrev_b32_e32 v121, 3, v89
	v_mov_b64_e32 v[30:31], s[6:7]
	s_movk_i32 s5, 0x1400
	v_ashrrev_i32_e32 v93, 31, v92
	v_ashrrev_i32_e32 v95, 31, v94
	v_or_b32_e32 v132, s2, v121
	v_lshlrev_b64 v[118:119], 11, v[98:99]
	v_mad_u64_u32 v[30:31], s[6:7], v98, s5, v[30:31]
	v_lshlrev_b64 v[114:115], 9, v[92:93]
	v_lshlrev_b64 v[116:117], 9, v[94:95]
	v_lshl_add_u64 v[28:29], s[12:13], 0, v[118:119]
	v_mad_i32_i24 v31, v99, s5, v31
	v_lshlrev_b32_e32 v108, 1, v132
	v_mov_b32_e32 v109, v1
	v_lshl_add_u64 v[22:23], v[20:21], 0, v[114:115]
	v_lshl_add_u64 v[24:25], v[20:21], 0, v[116:117]
	v_lshl_add_u64 v[28:29], v[28:29], 0, v[108:109]
	v_lshl_add_u64 v[30:31], v[30:31], 0, v[108:109]
	global_load_dwordx4 v[20:23], v[22:23], off
	s_nop 0
	global_load_dwordx4 v[24:27], v[24:25], off
	s_nop 0
	global_load_dwordx4 v[72:75], v[28:29], off
	global_load_dwordx4 v[32:35], v[28:29], off offset:64
	global_load_dwordx4 v[68:71], v[30:31], off offset:2048
	s_nop 0
	global_load_dwordx4 v[28:31], v[30:31], off offset:2112
	v_lshlrev_b32_e32 v188, 4, v102
	v_and_b32_e32 v188, 0xf0, v188
	v_mov_b32_e32 v189, 0
	v_add_u32_e32 v190, s4, v104
	v_ashrrev_i32_e32 v191, 31, v190
	v_lshlrev_b64 v[190:191], 11, v[190:191]
	v_lshl_add_u64 v[190:191], s[12:13], 0, v[190:191]
	v_lshl_add_u64 v[190:191], v[190:191], 0, s[2:3]
	v_lshl_add_u64 v[190:191], v[190:191], 0, v[188:189]
	s_mov_b32 s98, 0x10000
	s_mov_b32 s99, 0
	global_load_dwordx4 v[156:159], v[190:191], off offset:1536
	global_load_dwordx4 v[160:163], v[190:191], off offset:1024
	v_lshl_add_u64 v[190:191], v[190:191], 0, s[98:99]
	global_load_dwordx4 v[164:167], v[190:191], off offset:1536
	global_load_dwordx4 v[168:171], v[190:191], off offset:1024
	v_lshl_add_u64 v[190:191], v[190:191], 0, s[98:99]
	global_load_dwordx4 v[172:175], v[190:191], off offset:1536
	global_load_dwordx4 v[176:179], v[190:191], off offset:1024
	v_lshl_add_u64 v[190:191], v[190:191], 0, s[98:99]
	global_load_dwordx4 v[180:183], v[190:191], off offset:1536
	global_load_dwordx4 v[184:187], v[190:191], off offset:1024
	v_mov_b32_e32 v3, v201
	v_mov_b32_e32 v0, v201
	v_readlane_b32 s14, v253, 48
	v_ashrrev_i32_e32 v0, 6, v0
	v_cmp_gt_i32_e32 vcc, 4, v0
	v_readlane_b32 s15, v253, 49
	s_and_saveexec_b64 s[6:7], vcc
	s_cbranch_execz .LBB0_143
	v_readlane_b32 s10, v253, 42
	v_readlane_b32 s11, v253, 43
	s_load_dwordx2 s[10:11], s[10:11], 0x90
	v_add_u32_e32 v36, s8, v0
	v_readlane_b32 s5, v253, 58
	v_and_b32_e32 v3, 63, v3
	v_readlane_b32 s8, v254, 11
	v_add_u32_e32 v38, s5, v36
	v_ashrrev_i32_e32 v39, 31, v38
	s_waitcnt lgkmcnt(0)
	v_lshl_add_u64 v[38:39], v[38:39], 2, s[10:11]
	global_load_dword v42, v[38:39], off
	v_lshl_or_b32 v38, v3, 1, s4
	v_ashrrev_i32_e32 v39, 31, v38
	v_lshlrev_b64 v[40:41], 5, v[38:39]
	v_or_b32_e32 v38, 1, v38
	v_ashrrev_i32_e32 v39, 31, v38
	v_ashrrev_i32_e32 v37, 31, v36
	v_readlane_b32 s9, v254, 12
	v_lshlrev_b64 v[38:39], 5, v[38:39]
	v_lshlrev_b64 v[36:37], 2, v[36:37]
	v_lshl_add_u64 v[40:41], s[8:9], 0, v[40:41]
	v_lshl_add_u64 v[38:39], s[8:9], 0, v[38:39]
	v_lshl_add_u64 v[40:41], v[40:41], 0, v[36:37]
	v_lshl_add_u64 v[36:37], v[38:39], 0, v[36:37]
	global_load_dword v37, v[36:37], off
	s_nop 0
	global_load_dword v36, v[40:41], off
	v_and_b32_e32 v38, 64, v243
	v_add_u32_e32 v39, -1, v243
	v_cmp_lt_i32_e32 vcc, v39, v38
	v_add_u32_e32 v40, -2, v243
	v_add_u32_e32 v43, -4, v243
	v_cndmask_b32_e32 v39, v39, v243, vcc
	v_lshlrev_b32_e32 v39, 2, v39
	v_cmp_lt_i32_e32 vcc, v40, v38
	v_add_u32_e32 v44, -8, v243
	s_waitcnt vmcnt(2)
	v_mul_f32_e32 v41, 0x3fb8aa3b, v42
	v_exp_f32_e32 v41, v41
	v_cndmask_b32_e32 v40, v40, v243, vcc
	v_cmp_eq_u32_e32 vcc, 0, v3
	v_lshlrev_b32_e32 v40, 2, v40
	s_waitcnt vmcnt(1)
	v_mul_f32_e32 v42, v37, v41
	s_waitcnt vmcnt(0)
	v_fma_f32 v42, v36, -v41, -v42
	ds_bpermute_b32 v39, v39, v42
	s_waitcnt lgkmcnt(0)
	v_add_f32_e32 v39, v42, v39
	v_cndmask_b32_e32 v39, v39, v42, vcc
	ds_bpermute_b32 v40, v40, v39
	v_cmp_lt_i32_e32 vcc, v43, v38
	s_waitcnt lgkmcnt(0)
	v_add_f32_e32 v40, v39, v40
	v_cndmask_b32_e32 v43, v43, v243, vcc
	v_cmp_gt_u32_e32 vcc, 2, v3
	v_lshlrev_b32_e32 v43, 2, v43
	s_nop 0
	v_cndmask_b32_e32 v39, v40, v39, vcc
	ds_bpermute_b32 v40, v43, v39
	v_cmp_lt_i32_e32 vcc, v44, v38
	v_add_u32_e32 v43, -16, v243
	s_waitcnt lgkmcnt(0)
	v_add_f32_e32 v40, v39, v40
	v_cndmask_b32_e32 v44, v44, v243, vcc
	v_cmp_gt_u32_e32 vcc, 4, v3
	v_lshlrev_b32_e32 v44, 2, v44
	s_nop 0
	v_cndmask_b32_e32 v39, v40, v39, vcc
	ds_bpermute_b32 v40, v44, v39
	v_cmp_lt_i32_e32 vcc, v43, v38
	v_subrev_u32_e32 v44, 32, v243
	s_waitcnt lgkmcnt(0)
	v_add_f32_e32 v40, v39, v40
	v_cndmask_b32_e32 v43, v43, v243, vcc
	v_cmp_gt_u32_e32 vcc, 8, v3
	v_lshlrev_b32_e32 v43, 2, v43
	s_nop 0
	v_cndmask_b32_e32 v39, v40, v39, vcc
	ds_bpermute_b32 v40, v43, v39
	v_cmp_lt_i32_e32 vcc, v44, v38
	v_lshlrev_b32_e32 v43, 3, v3
	v_lshl_or_b32 v0, v0, 9, v43
	v_cndmask_b32_e32 v38, v44, v243, vcc
	s_waitcnt lgkmcnt(0)
	v_add_f32_e32 v40, v39, v40
	v_cmp_gt_u32_e32 vcc, 16, v3
	v_lshlrev_b32_e32 v38, 2, v38
	v_add_u32_e32 v0, 0, v0
	v_cndmask_b32_e32 v39, v40, v39, vcc
	ds_bpermute_b32 v38, v38, v39
	v_cmp_gt_u32_e32 vcc, 32, v3
	v_add_u32_e32 v40, 0x19800, v0
	v_add_u32_e32 v0, 0x1a000, v0
	s_waitcnt lgkmcnt(0)
	v_add_f32_e32 v38, v39, v38
	v_cndmask_b32_e32 v3, v38, v39, vcc
	v_sub_f32_e32 v3, v3, v42
	v_fma_f32 v38, v36, -v41, v3
	v_fma_f32 v39, v37, -v41, v38
	ds_write_b64 v40, v[38:39]
	ds_write_b64 v0, v[36:37]
.LBB0_143:
	s_or_b64 exec, exec, s[6:7]
	v_lshlrev_b32_e32 v0, 4, v102
	v_and_b32_e32 v0, 0xf0, v0
	v_add_u32_e32 v40, 0, v0
	s_movk_i32 s8, 0x110
	v_mad_u64_u32 v[44:45], s[6:7], v104, s8, v[40:41]
	v_lshlrev_b32_e32 v120, 1, v121
	v_add_u32_e32 v93, 0, v120
	v_cmp_lt_i32_e32 vcc, -1, v100
	v_mad_u32_u24 v95, v101, s8, v93
	v_readlane_b32 s14, v253, 48
	v_readlane_b32 s15, v253, 49
	v_mov_b32_e32 v154, v44
	v_mad_u64_u32 v[44:45], s[6:7], v106, s8, v[40:41]
	v_ashrrev_i32_e32 v36, 4, v2
	v_mad_u64_u32 v[42:43], s[6:7], v36, s8, v[40:41]
	v_ashrrev_i32_e32 v36, 4, v91
	v_mad_u64_u32 v[40:41], s[4:5], v36, s8, v[40:41]
	v_mul_lo_u32 v0, v80, s8
	v_add_u32_e32 v81, 0, v0
	v_add_u32_e32 v109, v81, v120
	v_mov_b32_e32 v0, v1
	v_mov_b32_e32 v2, v1
	v_mov_b32_e32 v3, v1
	v_readlane_b32 s12, v253, 46
	v_readlane_b32 s13, v253, 47
	s_waitcnt vmcnt(7)
	ds_write_b128 v154, v[156:159]
	s_waitcnt vmcnt(6)
	ds_write_b128 v154, v[160:163] offset:34816
	s_waitcnt vmcnt(5)
	ds_write_b128 v44, v[164:167]
	s_waitcnt vmcnt(4)
	ds_write_b128 v44, v[168:171] offset:34816
	s_waitcnt vmcnt(3)
	ds_write_b128 v42, v[172:175]
	s_waitcnt vmcnt(2)
	ds_write_b128 v42, v[176:179] offset:34816
	s_waitcnt vmcnt(1)
	ds_write_b128 v40, v[180:183]
	s_waitcnt vmcnt(0)
	ds_write_b128 v40, v[184:187] offset:34816
	s_waitcnt lgkmcnt(0)
	s_barrier
	ds_read_b128 v[76:79], v109
	v_mov_b64_e32 v[38:39], v[2:3]
	v_mov_b64_e32 v[36:37], v[0:1]
	s_and_saveexec_b64 s[4:5], vcc
	s_cbranch_execz .LBB0_145
	ds_read_b128 v[36:39], v95 offset:34816
	s_waitcnt lgkmcnt(0)
	v_mfma_f32_16x16x32_bf16 v[36:39], v[36:39], v[76:79], 0

.LBB0_316:
	s_cmpk_gt_i32 s24, 0x7f
	s_mov_b64 s[4:5], -1
	s_cbranch_scc0 .LBB0_399
	s_cmpk_gt_u32 s24, 0x9f
	s_cbranch_scc0 .LBB0_323
	v_mov_b32_e32 v18, v201
	v_mov_b32_e32 v0, v201
	v_mov_b32_e32 v2, v201
	s_add_i32 s6, s24, 0xffffff60
	s_barrier
	s_lshl_b32 s2, s6, 6
	v_ashrrev_i32_e32 v2, 6, v2
	s_and_b32 s7, s24, 1
	s_and_b32 s2, s2, 0x7f80
	v_readlane_b32 s98, v253, 46
	v_readlane_b32 s99, v253, 47
	v_and_b32_e32 v146, 0x7f, v201
	v_or_b32_e32 v146, s2, v146
	v_lshlrev_b32_e32 v146, 11, v146
	v_mov_b32_e32 v147, 0
	v_lshl_add_u64 v[146:147], s[98:99], 0, v[146:147]
	v_lshrrev_b32_e32 v144, 7, v201
	v_lshlrev_b32_e32 v144, 4, v144
	v_mov_b32_e32 v145, 0
	v_lshl_add_u64 v[146:147], v[146:147], 0, v[144:145]
	s_lshl_b32 s98, s7, 8
	s_mov_b32 s99, 0
	v_lshl_add_u64 v[144:145], v[146:147], 0, s[98:99]
	global_load_dwordx4 v[96:99], v[144:145], off offset:1024
	global_load_dwordx4 v[100:103], v[144:145], off offset:1088
	global_load_dwordx4 v[104:107], v[144:145], off offset:1152
	global_load_dwordx4 v[108:111], v[144:145], off offset:1216
	s_lshl_b32 s98, s7, 9
	v_lshl_add_u64 v[144:145], v[146:147], 0, s[98:99]
	global_load_dwordx4 v[112:115], v[144:145], off
	global_load_dwordx4 v[116:119], v[144:145], off offset:64
	global_load_dwordx4 v[120:123], v[144:145], off offset:128
	global_load_dwordx4 v[124:127], v[144:145], off offset:192
	global_load_dwordx4 v[128:131], v[144:145], off offset:256
	global_load_dwordx4 v[132:135], v[144:145], off offset:320
	global_load_dwordx4 v[136:139], v[144:145], off offset:384
	global_load_dwordx4 v[140:143], v[144:145], off offset:448
	v_cmp_gt_i32_e32 vcc, 4, v2
	s_and_saveexec_b64 s[4:5], vcc
	s_cbranch_execz .LBB0_320
	v_readlane_b32 s8, v253, 42
	v_readlane_b32 s9, v253, 43
	s_load_dwordx2 s[8:9], s[8:9], 0x90
	v_lshl_add_u32 v4, s7, 2, v2
	v_readlane_b32 s10, v253, 58
	v_and_b32_e32 v3, 63, v0
	v_ashrrev_i32_e32 v5, 31, v4
	v_add_u32_e32 v6, s10, v4
	v_ashrrev_i32_e32 v7, 31, v6
	s_waitcnt lgkmcnt(0)
	v_lshl_add_u64 v[6:7], v[6:7], 2, s[8:9]
	global_load_dword v8, v[6:7], off
	s_lshl_b32 s8, s2, 5
	v_lshl_or_b32 v0, v3, 6, s8
	v_readlane_b32 s8, v254, 11
	v_readlane_b32 s9, v254, 12
	v_add_u32_e32 v10, -4, v243
	v_add_u32_e32 v11, -8, v243
	v_lshl_add_u64 v[6:7], s[8:9], 0, v[0:1]
	v_lshl_add_u64 v[4:5], v[4:5], 2, v[6:7]
	global_load_dword v7, v[4:5], off offset:32
	global_load_dword v6, v[4:5], off
	v_and_b32_e32 v0, 64, v243
	v_add_u32_e32 v4, -1, v243
	v_cmp_lt_i32_e32 vcc, v4, v0
	v_add_u32_e32 v5, -2, v243
	s_waitcnt vmcnt(2)
	v_mul_f32_e32 v8, 0x3fb8aa3b, v8
	v_exp_f32_e32 v8, v8
	v_cndmask_b32_e32 v4, v4, v243, vcc
	v_lshlrev_b32_e32 v4, 2, v4
	v_cmp_lt_i32_e32 vcc, v5, v0
	s_waitcnt vmcnt(1)
	v_mul_f32_e32 v9, v7, v8
	s_waitcnt vmcnt(0)
	v_fma_f32 v9, v6, -v8, -v9
	ds_bpermute_b32 v4, v4, v9
	v_cndmask_b32_e32 v5, v5, v243, vcc
	v_cmp_eq_u32_e32 vcc, 0, v3
	v_lshlrev_b32_e32 v5, 2, v5
	s_waitcnt lgkmcnt(0)
	v_add_f32_e32 v4, v9, v4
	v_cndmask_b32_e32 v4, v4, v9, vcc
	ds_bpermute_b32 v5, v5, v4
	v_cmp_lt_i32_e32 vcc, v10, v0
	s_waitcnt lgkmcnt(0)
	v_add_f32_e32 v5, v4, v5
	v_cndmask_b32_e32 v10, v10, v243, vcc
	v_cmp_gt_u32_e32 vcc, 2, v3
	v_lshlrev_b32_e32 v10, 2, v10
	s_nop 0
	v_cndmask_b32_e32 v4, v5, v4, vcc
	ds_bpermute_b32 v5, v10, v4
	v_cmp_lt_i32_e32 vcc, v11, v0
	v_add_u32_e32 v10, -16, v243
	s_waitcnt lgkmcnt(0)
	v_add_f32_e32 v5, v4, v5
	v_cndmask_b32_e32 v11, v11, v243, vcc
	v_cmp_gt_u32_e32 vcc, 4, v3
	v_lshlrev_b32_e32 v11, 2, v11
	s_nop 0
	v_cndmask_b32_e32 v4, v5, v4, vcc
	ds_bpermute_b32 v5, v11, v4
	v_cmp_lt_i32_e32 vcc, v10, v0
	v_subrev_u32_e32 v11, 32, v243
	s_waitcnt lgkmcnt(0)
	v_add_f32_e32 v5, v4, v5
	v_cndmask_b32_e32 v10, v10, v243, vcc
	v_cmp_gt_u32_e32 vcc, 8, v3
	v_lshlrev_b32_e32 v10, 2, v10
	s_nop 0
	v_cndmask_b32_e32 v4, v5, v4, vcc
	ds_bpermute_b32 v5, v10, v4
	v_cmp_lt_i32_e32 vcc, v11, v0
	v_lshlrev_b32_e32 v10, 3, v3
	v_lshl_or_b32 v2, v2, 9, v10
	v_cndmask_b32_e32 v0, v11, v243, vcc
	s_waitcnt lgkmcnt(0)
	v_add_f32_e32 v5, v4, v5
	v_cmp_gt_u32_e32 vcc, 16, v3
	v_lshlrev_b32_e32 v0, 2, v0
	v_add_u32_e32 v2, 0, v2
	v_cndmask_b32_e32 v4, v5, v4, vcc
	ds_bpermute_b32 v0, v0, v4
	v_cmp_gt_u32_e32 vcc, 32, v3
	v_add_u32_e32 v5, 0x19800, v2
	v_add_u32_e32 v10, 0x1a000, v2
	s_waitcnt lgkmcnt(0)
	v_add_f32_e32 v0, v4, v0
	v_cndmask_b32_e32 v0, v0, v4, vcc
	v_sub_f32_e32 v0, v0, v9
	v_fma_f32 v2, v6, -v8, v0
	v_fma_f32 v3, v7, -v8, v2
	ds_write_b64 v5, v[2:3]
	ds_write_b64 v10, v[6:7]

.LBB0_322:
	s_or_b64 exec, exec, s[4:5]
	s_waitcnt lgkmcnt(1)
	v_sub_f32_e32 v3, v3, v4
	v_mul_f32_e32 v3, 0x3fb8aa3b, v3
	v_exp_f32_e32 v3, v3
	v_and_b32_e32 v28, 0x7f, v18
	s_waitcnt lgkmcnt(0)
	s_barrier
	v_mul_f32_e32 v2, v2, v3
	ds_write_b32 v0, v2
	v_or_b32_e32 v0, s2, v28
	v_readlane_b32 s8, v253, 46
	v_ashrrev_i32_e32 v2, 4, v18
	v_lshlrev_b32_e32 v0, 11, v0
	v_readlane_b32 s9, v253, 47
	v_and_b32_e32 v6, -8, v2
	s_lshl_b32 s2, s7, 8
	v_lshl_add_u64 v[24:25], s[8:9], 0, v[0:1]
	v_ashrrev_i32_e32 v7, 31, v6
	v_lshl_add_u64 v[20:21], v[24:25], 0, s[2:3]
	v_lshlrev_b64 v[26:27], 1, v[6:7]
	v_lshl_add_u64 v[2:3], v[20:21], 0, v[26:27]
	s_waitcnt lgkmcnt(0)
	s_barrier
	v_lshl_add_u32 v0, v28, 1, 0
	s_movk_i32 s8, 0x110
	v_mad_u64_u32 v[16:17], s[4:5], v6, s8, v[0:1]
	v_add_u32_e32 v29, 0x200, v18
	v_add_u32_e32 v17, 0x400, v18
	s_lshl_b32 s2, s7, 9
	v_and_b32_e32 v19, 15, v18
	v_readlane_b32 s10, v253, 48
	v_readlane_b32 s11, v253, 49
	s_waitcnt vmcnt(11)
	v_mov_b64_e32 v[2:3], v[96:97]
	v_mov_b64_e32 v[4:5], v[98:99]
	ds_write_b16 v16, v2
	ds_write_b16_d16_hi v16, v2 offset:272
	ds_write_b16 v16, v3 offset:544
	ds_write_b16_d16_hi v16, v3 offset:816
	ds_write_b16 v16, v4 offset:1088
	ds_write_b16_d16_hi v16, v4 offset:1360
	ds_write_b16 v16, v5 offset:1632
	ds_write_b16_d16_hi v16, v5 offset:1904
	v_ashrrev_i32_e32 v2, 4, v29
	v_and_b32_e32 v6, -8, v2
	v_ashrrev_i32_e32 v7, 31, v6
	v_lshlrev_b64 v[14:15], 1, v[6:7]
	v_lshl_add_u64 v[2:3], v[20:21], 0, v[14:15]
	v_mad_u64_u32 v[12:13], s[4:5], v6, s8, v[0:1]
	v_add_u32_e32 v13, 0x600, v18
	s_waitcnt vmcnt(10)
	v_mov_b64_e32 v[2:3], v[100:101]
	v_mov_b64_e32 v[4:5], v[102:103]
	ds_write_b16 v12, v2
	ds_write_b16_d16_hi v12, v2 offset:272
	ds_write_b16 v12, v3 offset:544
	ds_write_b16_d16_hi v12, v3 offset:816
	ds_write_b16 v12, v4 offset:1088
	ds_write_b16_d16_hi v12, v4 offset:1360
	ds_write_b16 v12, v5 offset:1632
	ds_write_b16_d16_hi v12, v5 offset:1904
	v_ashrrev_i32_e32 v2, 4, v17
	v_and_b32_e32 v6, -8, v2
	v_ashrrev_i32_e32 v7, 31, v6
	v_lshlrev_b64 v[10:11], 1, v[6:7]
	v_lshl_add_u64 v[2:3], v[20:21], 0, v[10:11]
	v_mad_u64_u32 v[8:9], s[4:5], v6, s8, v[0:1]
	s_waitcnt vmcnt(9)
	v_mov_b64_e32 v[2:3], v[104:105]
	v_mov_b64_e32 v[4:5], v[106:107]
	ds_write_b16 v8, v2
	ds_write_b16_d16_hi v8, v2 offset:272
	ds_write_b16 v8, v3 offset:544
	ds_write_b16_d16_hi v8, v3 offset:816
	ds_write_b16 v8, v4 offset:1088
	ds_write_b16_d16_hi v8, v4 offset:1360
	ds_write_b16 v8, v5 offset:1632
	ds_write_b16_d16_hi v8, v5 offset:1904
	v_ashrrev_i32_e32 v2, 4, v13
	v_and_b32_e32 v2, -8, v2
	v_ashrrev_i32_e32 v3, 31, v2
	v_lshlrev_b64 v[6:7], 1, v[2:3]
	v_lshl_add_u64 v[4:5], v[20:21], 0, v[6:7]
	v_mad_u64_u32 v[4:5], s[4:5], v2, s8, v[0:1]
	v_lshl_add_u64 v[2:3], v[24:25], 0, s[2:3]
	v_ashrrev_i32_e32 v5, 3, v18
	s_add_i32 s2, 0, 0x1a000
	v_lshlrev_b32_e32 v5, 2, v5
	v_lshl_add_u32 v9, v28, 2, s2
	v_and_b32_e32 v5, 0xfffffe00, v5
	v_add_u32_e32 v5, v9, v5
	v_lshl_add_u64 v[14:15], v[2:3], 0, v[14:15]
	v_lshl_add_u64 v[10:11], v[2:3], 0, v[10:11]
	v_lshl_add_u64 v[6:7], v[2:3], 0, v[6:7]
	s_mov_b32 s2, 0xfffffe0
	s_waitcnt vmcnt(8)
	v_mov_b64_e32 v[20:21], v[108:109]
	v_mov_b64_e32 v[22:23], v[110:111]
	ds_write_b16 v4, v20
	ds_write_b16_d16_hi v4, v20 offset:272
	ds_write_b16 v4, v21 offset:544
	ds_write_b16_d16_hi v4, v21 offset:816
	ds_write_b16 v4, v22 offset:1088
	ds_write_b16_d16_hi v4, v22 offset:1360
	ds_write_b16 v4, v23 offset:1632
	ds_write_b16_d16_hi v4, v23 offset:1904
	v_lshl_add_u64 v[20:21], v[2:3], 0, v[26:27]
	ds_read_b32 v5, v5
	s_waitcnt vmcnt(7)
	v_mov_b64_e32 v[20:21], v[112:113]
	v_mov_b64_e32 v[22:23], v[114:115]
	v_lshlrev_b32_e32 v24, 16, v20
	v_and_b32_e32 v20, 0xffff0000, v20
	s_waitcnt lgkmcnt(0)
	v_mul_f32_e32 v20, v5, v20
	v_cvt_pk_bf16_f32 v20, v20, v1
	ds_write_b16 v16, v20 offset:35088
	v_lshlrev_b32_e32 v20, 16, v21
	v_mul_f32_e32 v20, v5, v20
	v_cvt_pk_bf16_f32 v20, v20, v1
	ds_write_b16 v16, v20 offset:35360
	v_and_b32_e32 v20, 0xffff0000, v21
	v_mul_f32_e32 v20, v5, v20
	v_cvt_pk_bf16_f32 v20, v20, v1
	ds_write_b16 v16, v20 offset:35632
	v_lshlrev_b32_e32 v20, 16, v22
	v_mul_f32_e32 v20, v5, v20
	v_cvt_pk_bf16_f32 v20, v20, v1
	ds_write_b16 v16, v20 offset:35904
	v_and_b32_e32 v20, 0xffff0000, v22
	v_mul_f32_e32 v20, v5, v20
	v_cvt_pk_bf16_f32 v20, v20, v1
	ds_write_b16 v16, v20 offset:36176
	v_lshlrev_b32_e32 v20, 16, v23
	v_mul_f32_e32 v20, v5, v20
	v_cvt_pk_bf16_f32 v20, v20, v1
	ds_write_b16 v16, v20 offset:36448
	v_and_b32_e32 v20, 0xffff0000, v23
	v_mul_f32_e32 v24, v5, v24
	v_mul_f32_e32 v5, v5, v20
	v_cvt_pk_bf16_f32 v5, v5, v1
	ds_write_b16 v16, v5 offset:36720
	v_ashrrev_i32_e32 v5, 3, v29
	v_lshlrev_b32_e32 v5, 2, v5
	v_and_b32_e32 v5, 0xfffffe00, v5
	v_add_u32_e32 v5, v9, v5
	ds_read_b32 v5, v5
	v_cvt_pk_bf16_f32 v24, v24, v1
	ds_write_b16 v16, v24 offset:34816
	s_waitcnt vmcnt(6)
	v_mov_b64_e32 v[20:21], v[116:117]
	v_mov_b64_e32 v[22:23], v[118:119]
	v_lshlrev_b32_e32 v14, 16, v20
	s_waitcnt lgkmcnt(1)
	v_mul_f32_e32 v14, v5, v14
	v_cvt_pk_bf16_f32 v14, v14, v1
	ds_write_b16 v12, v14 offset:34816
	v_and_b32_e32 v14, 0xffff0000, v20
	v_mul_f32_e32 v14, v5, v14
	v_cvt_pk_bf16_f32 v14, v14, v1
	ds_write_b16 v12, v14 offset:35088
	v_lshlrev_b32_e32 v14, 16, v21
	v_mul_f32_e32 v14, v5, v14
	v_cvt_pk_bf16_f32 v14, v14, v1
	ds_write_b16 v12, v14 offset:35360
	v_and_b32_e32 v14, 0xffff0000, v21
	v_mul_f32_e32 v14, v5, v14
	v_cvt_pk_bf16_f32 v14, v14, v1
	ds_write_b16 v12, v14 offset:35632
	v_lshlrev_b32_e32 v14, 16, v22
	v_mul_f32_e32 v14, v5, v14
	v_cvt_pk_bf16_f32 v14, v14, v1
	ds_write_b16 v12, v14 offset:35904
	v_and_b32_e32 v14, 0xffff0000, v22
	v_mul_f32_e32 v14, v5, v14
	v_cvt_pk_bf16_f32 v14, v14, v1
	ds_write_b16 v12, v14 offset:36176
	v_lshlrev_b32_e32 v14, 16, v23
	v_mul_f32_e32 v14, v5, v14
	v_cvt_pk_bf16_f32 v14, v14, v1
	ds_write_b16 v12, v14 offset:36448
	v_and_b32_e32 v14, 0xffff0000, v23
	v_mul_f32_e32 v5, v5, v14
	v_cvt_pk_bf16_f32 v5, v5, v1
	ds_write_b16 v12, v5 offset:36720
	v_ashrrev_i32_e32 v5, 3, v17
	v_lshlrev_b32_e32 v5, 2, v5
	v_and_b32_e32 v5, 0xfffffe00, v5
	v_add_u32_e32 v5, v9, v5
	ds_read_b32 v5, v5
	v_ashrrev_i32_e32 v12, 1, v18
	s_waitcnt vmcnt(5)
	v_mov_b64_e32 v[20:21], v[120:121]
	v_mov_b64_e32 v[22:23], v[122:123]
	v_lshlrev_b32_e32 v10, 16, v20
	s_waitcnt lgkmcnt(0)
	v_mul_f32_e32 v10, v5, v10
	v_cvt_pk_bf16_f32 v10, v10, v1
	ds_write_b16 v8, v10 offset:34816
	v_and_b32_e32 v10, 0xffff0000, v20
	v_mul_f32_e32 v10, v5, v10
	v_cvt_pk_bf16_f32 v10, v10, v1
	ds_write_b16 v8, v10 offset:35088
	v_lshlrev_b32_e32 v10, 16, v21
	v_mul_f32_e32 v10, v5, v10
	v_cvt_pk_bf16_f32 v10, v10, v1
	ds_write_b16 v8, v10 offset:35360
	v_and_b32_e32 v10, 0xffff0000, v21
	v_mul_f32_e32 v10, v5, v10
	v_cvt_pk_bf16_f32 v10, v10, v1
	ds_write_b16 v8, v10 offset:35632
	v_lshlrev_b32_e32 v10, 16, v22
	v_mul_f32_e32 v10, v5, v10
	v_cvt_pk_bf16_f32 v10, v10, v1
	ds_write_b16 v8, v10 offset:35904
	v_and_b32_e32 v10, 0xffff0000, v22
	v_mul_f32_e32 v10, v5, v10
	v_cvt_pk_bf16_f32 v10, v10, v1
	ds_write_b16 v8, v10 offset:36176
	v_lshlrev_b32_e32 v10, 16, v23
	v_mul_f32_e32 v10, v5, v10
	v_cvt_pk_bf16_f32 v10, v10, v1
	ds_write_b16 v8, v10 offset:36448
	v_and_b32_e32 v10, 0xffff0000, v23
	v_mul_f32_e32 v5, v5, v10
	v_cvt_pk_bf16_f32 v5, v5, v1
	ds_write_b16 v8, v5 offset:36720
	v_ashrrev_i32_e32 v5, 3, v13
	v_lshlrev_b32_e32 v5, 2, v5
	v_and_b32_e32 v5, 0xfffffe00, v5
	v_add_u32_e32 v5, v9, v5
	ds_read_b32 v5, v5
	s_waitcnt vmcnt(4)
	v_mov_b64_e32 v[14:15], v[124:125]
	v_mov_b64_e32 v[16:17], v[126:127]
	v_lshlrev_b32_e32 v6, 16, v14
	v_add_u32_e32 v8, 0x800, v18
	s_waitcnt lgkmcnt(0)
	v_mul_f32_e32 v6, v5, v6
	v_cvt_pk_bf16_f32 v6, v6, v1
	ds_write_b16 v4, v6 offset:34816
	v_and_b32_e32 v6, 0xffff0000, v14
	v_mul_f32_e32 v6, v5, v6
	v_cvt_pk_bf16_f32 v6, v6, v1
	ds_write_b16 v4, v6 offset:35088
	v_lshlrev_b32_e32 v6, 16, v15
	v_mul_f32_e32 v6, v5, v6
	v_cvt_pk_bf16_f32 v6, v6, v1
	ds_write_b16 v4, v6 offset:35360
	v_and_b32_e32 v6, 0xffff0000, v15
	v_mul_f32_e32 v6, v5, v6
	v_cvt_pk_bf16_f32 v6, v6, v1
	ds_write_b16 v4, v6 offset:35632
	v_lshlrev_b32_e32 v6, 16, v16
	v_mul_f32_e32 v6, v5, v6
	v_cvt_pk_bf16_f32 v6, v6, v1
	ds_write_b16 v4, v6 offset:35904
	v_and_b32_e32 v6, 0xffff0000, v16
	v_mul_f32_e32 v6, v5, v6
	v_cvt_pk_bf16_f32 v6, v6, v1
	ds_write_b16 v4, v6 offset:36176
	v_lshlrev_b32_e32 v6, 16, v17
	v_mul_f32_e32 v6, v5, v6
	v_cvt_pk_bf16_f32 v6, v6, v1
	ds_write_b16 v4, v6 offset:36448
	v_and_b32_e32 v6, 0xffff0000, v17
	v_mul_f32_e32 v5, v5, v6
	v_cvt_pk_bf16_f32 v5, v5, v1
	ds_write_b16 v4, v5 offset:36720
	v_ashrrev_i32_e32 v4, 4, v8
	v_and_b32_e32 v10, -8, v4
	v_ashrrev_i32_e32 v11, 31, v10
	v_lshl_add_u64 v[4:5], v[10:11], 1, v[2:3]
	v_ashrrev_i32_e32 v8, 3, v8
	v_lshlrev_b32_e32 v8, 2, v8
	v_and_b32_e32 v8, 0xfffffe00, v8
	v_add_u32_e32 v8, v9, v8
	ds_read_b32 v8, v8
	v_mad_u64_u32 v[10:11], s[4:5], v10, s8, v[0:1]
	s_waitcnt vmcnt(3)
	v_mov_b64_e32 v[4:5], v[128:129]
	v_mov_b64_e32 v[6:7], v[130:131]
	v_lshlrev_b32_e32 v11, 16, v4
	v_and_b32_e32 v4, 0xffff0000, v4
	s_waitcnt lgkmcnt(0)
	v_mul_f32_e32 v4, v8, v4
	v_cvt_pk_bf16_f32 v4, v4, v1
	ds_write_b16 v10, v4 offset:35088
	v_lshlrev_b32_e32 v4, 16, v5
	v_mul_f32_e32 v4, v8, v4
	v_cvt_pk_bf16_f32 v4, v4, v1
	ds_write_b16 v10, v4 offset:35360
	v_and_b32_e32 v4, 0xffff0000, v5
	v_mul_f32_e32 v4, v8, v4
	v_cvt_pk_bf16_f32 v4, v4, v1
	ds_write_b16 v10, v4 offset:35632
	v_lshlrev_b32_e32 v4, 16, v6
	v_mul_f32_e32 v4, v8, v4
	v_cvt_pk_bf16_f32 v4, v4, v1
	ds_write_b16 v10, v4 offset:35904
	v_and_b32_e32 v4, 0xffff0000, v6
	v_mul_f32_e32 v4, v8, v4
	v_cvt_pk_bf16_f32 v4, v4, v1
	ds_write_b16 v10, v4 offset:36176
	v_lshlrev_b32_e32 v4, 16, v7
	v_mul_f32_e32 v4, v8, v4
	v_cvt_pk_bf16_f32 v4, v4, v1
	ds_write_b16 v10, v4 offset:36448
	v_and_b32_e32 v4, 0xffff0000, v7
	v_mul_f32_e32 v4, v8, v4
	v_mul_f32_e32 v11, v8, v11
	v_cvt_pk_bf16_f32 v4, v4, v1
	v_add_u32_e32 v8, 0xa00, v18
	ds_write_b16 v10, v4 offset:36720
	v_ashrrev_i32_e32 v4, 4, v8
	v_cvt_pk_bf16_f32 v11, v11, v1
	ds_write_b16 v10, v11 offset:34816
	v_and_b32_e32 v10, -8, v4
	v_ashrrev_i32_e32 v11, 31, v10
	v_lshl_add_u64 v[4:5], v[10:11], 1, v[2:3]
	v_ashrrev_i32_e32 v8, 3, v8
	v_lshlrev_b32_e32 v8, 2, v8
	v_and_b32_e32 v8, 0xfffffe00, v8
	v_add_u32_e32 v8, v9, v8
	ds_read_b32 v8, v8
	v_mad_u64_u32 v[10:11], s[4:5], v10, s8, v[0:1]
	s_waitcnt vmcnt(2)
	v_mov_b64_e32 v[4:5], v[132:133]
	v_mov_b64_e32 v[6:7], v[134:135]
	v_lshlrev_b32_e32 v11, 16, v4
	v_and_b32_e32 v4, 0xffff0000, v4
	s_waitcnt lgkmcnt(0)
	v_mul_f32_e32 v4, v8, v4
	v_cvt_pk_bf16_f32 v4, v4, v1
	ds_write_b16 v10, v4 offset:35088
	v_lshlrev_b32_e32 v4, 16, v5
	v_mul_f32_e32 v4, v8, v4
	v_cvt_pk_bf16_f32 v4, v4, v1
	ds_write_b16 v10, v4 offset:35360
	v_and_b32_e32 v4, 0xffff0000, v5
	v_mul_f32_e32 v4, v8, v4
	v_cvt_pk_bf16_f32 v4, v4, v1
	ds_write_b16 v10, v4 offset:35632
	v_lshlrev_b32_e32 v4, 16, v6
	v_mul_f32_e32 v4, v8, v4
	v_cvt_pk_bf16_f32 v4, v4, v1
	ds_write_b16 v10, v4 offset:35904
	v_and_b32_e32 v4, 0xffff0000, v6
	v_mul_f32_e32 v4, v8, v4
	v_cvt_pk_bf16_f32 v4, v4, v1
	ds_write_b16 v10, v4 offset:36176
	v_lshlrev_b32_e32 v4, 16, v7
	v_mul_f32_e32 v4, v8, v4
	v_cvt_pk_bf16_f32 v4, v4, v1
	ds_write_b16 v10, v4 offset:36448
	v_and_b32_e32 v4, 0xffff0000, v7
	v_mul_f32_e32 v4, v8, v4
	v_mul_f32_e32 v11, v8, v11
	v_cvt_pk_bf16_f32 v4, v4, v1
	v_add_u32_e32 v8, 0xc00, v18
	ds_write_b16 v10, v4 offset:36720
	v_ashrrev_i32_e32 v4, 4, v8
	v_cvt_pk_bf16_f32 v11, v11, v1
	ds_write_b16 v10, v11 offset:34816
	v_and_b32_e32 v10, -8, v4
	v_ashrrev_i32_e32 v11, 31, v10
	v_lshl_add_u64 v[4:5], v[10:11], 1, v[2:3]
	v_ashrrev_i32_e32 v8, 3, v8
	v_lshlrev_b32_e32 v8, 2, v8
	v_and_b32_e32 v8, 0xfffffe00, v8
	v_add_u32_e32 v8, v9, v8
	ds_read_b32 v8, v8
	v_mad_u64_u32 v[10:11], s[4:5], v10, s8, v[0:1]
	s_waitcnt vmcnt(1)
	v_mov_b64_e32 v[4:5], v[136:137]
	v_mov_b64_e32 v[6:7], v[138:139]
	v_lshlrev_b32_e32 v11, 16, v4
	v_and_b32_e32 v4, 0xffff0000, v4
	s_waitcnt lgkmcnt(0)
	v_mul_f32_e32 v4, v8, v4
	v_cvt_pk_bf16_f32 v4, v4, v1
	ds_write_b16 v10, v4 offset:35088
	v_lshlrev_b32_e32 v4, 16, v5
	v_mul_f32_e32 v4, v8, v4
	v_cvt_pk_bf16_f32 v4, v4, v1
	ds_write_b16 v10, v4 offset:35360
	v_and_b32_e32 v4, 0xffff0000, v5
	v_mul_f32_e32 v4, v8, v4
	v_cvt_pk_bf16_f32 v4, v4, v1
	ds_write_b16 v10, v4 offset:35632
	v_lshlrev_b32_e32 v4, 16, v6
	v_mul_f32_e32 v4, v8, v4
	v_cvt_pk_bf16_f32 v4, v4, v1
	ds_write_b16 v10, v4 offset:35904
	v_and_b32_e32 v4, 0xffff0000, v6
	v_mul_f32_e32 v4, v8, v4
	v_cvt_pk_bf16_f32 v4, v4, v1
	ds_write_b16 v10, v4 offset:36176
	v_lshlrev_b32_e32 v4, 16, v7
	v_mul_f32_e32 v4, v8, v4
	v_cvt_pk_bf16_f32 v4, v4, v1
	ds_write_b16 v10, v4 offset:36448
	v_and_b32_e32 v4, 0xffff0000, v7
	v_mul_f32_e32 v4, v8, v4
	v_mul_f32_e32 v11, v8, v11
	v_cvt_pk_bf16_f32 v4, v4, v1
	v_add_u32_e32 v8, 0xe00, v18
	ds_write_b16 v10, v4 offset:36720
	v_ashrrev_i32_e32 v4, 4, v8
	v_and_b32_e32 v6, -8, v4
	v_ashrrev_i32_e32 v7, 31, v6
	v_lshl_add_u64 v[2:3], v[6:7], 1, v[2:3]
	v_ashrrev_i32_e32 v7, 3, v8
	v_lshlrev_b32_e32 v7, 2, v7
	v_and_b32_e32 v7, 0xfffffe00, v7
	v_add_u32_e32 v7, v9, v7
	ds_read_b32 v8, v7
	v_mad_u64_u32 v[6:7], s[4:5], v6, s8, v[0:1]
	v_cvt_pk_bf16_f32 v11, v11, v1
	ds_write_b16 v10, v11 offset:34816
	s_waitcnt vmcnt(0)
	v_mov_b64_e32 v[2:3], v[140:141]
	v_mov_b64_e32 v[4:5], v[142:143]
	v_lshlrev_b32_e32 v0, 16, v2
	s_waitcnt lgkmcnt(1)
	v_mul_f32_e32 v0, v8, v0
	v_cvt_pk_bf16_f32 v0, v0, v1
	ds_write_b16 v6, v0 offset:34816
	v_and_b32_e32 v0, 0xffff0000, v2
	v_mul_f32_e32 v0, v8, v0
	v_cvt_pk_bf16_f32 v0, v0, v1
	ds_write_b16 v6, v0 offset:35088
	v_lshlrev_b32_e32 v0, 16, v3
	v_mul_f32_e32 v0, v8, v0
	v_cvt_pk_bf16_f32 v0, v0, v1
	ds_write_b16 v6, v0 offset:35360
	v_and_b32_e32 v0, 0xffff0000, v3
	v_mul_f32_e32 v0, v8, v0
	v_cvt_pk_bf16_f32 v0, v0, v1
	ds_write_b16 v6, v0 offset:35632
	v_lshlrev_b32_e32 v0, 16, v4
	v_mul_f32_e32 v0, v8, v0
	v_cvt_pk_bf16_f32 v0, v0, v1
	ds_write_b16 v6, v0 offset:35904
	v_and_b32_e32 v0, 0xffff0000, v4
	v_mul_f32_e32 v0, v8, v0
	v_cvt_pk_bf16_f32 v0, v0, v1
	ds_write_b16 v6, v0 offset:36176
	v_lshlrev_b32_e32 v0, 16, v5
	v_mul_f32_e32 v0, v8, v0
	v_cvt_pk_bf16_f32 v0, v0, v1
	ds_write_b16 v6, v0 offset:36448
	v_and_b32_e32 v0, 0xffff0000, v5
	v_mul_f32_e32 v0, v8, v0
	v_cvt_pk_bf16_f32 v0, v0, v1
	ds_write_b16 v6, v0 offset:36720
	v_and_b32_e32 v0, 48, v18
	v_and_or_b32 v2, v12, s2, v19
	v_add_u32_e32 v14, 0, v0
	v_mad_u64_u32 v[10:11], s[4:5], v2, s8, v[14:15]
	v_mad_u32_u24 v11, v19, s8, v14
	s_waitcnt lgkmcnt(0)
	s_barrier
	ds_read_b128 v[2:5], v10 offset:34816
	ds_read_b128 v[6:9], v10 offset:39168
	ds_read_b128 v[14:17], v11
	ds_read_b128 v[24:27], v11 offset:4352
	ds_read_b128 v[32:35], v11 offset:8704
	ds_read_b128 v[40:43], v11 offset:13056
	ds_read_b128 v[48:51], v11 offset:17408
	ds_read_b128 v[56:59], v11 offset:21760
	ds_read_b128 v[64:67], v11 offset:26112
	ds_read_b128 v[72:75], v11 offset:30464
	s_waitcnt lgkmcnt(7)
	v_mfma_f32_16x16x32_bf16 v[20:23], v[14:17], v[2:5], 0
	v_readlane_b32 s4, v254, 9
	v_readlane_b32 s5, v254, 10
	v_mfma_f32_16x16x32_bf16 v[14:17], v[14:17], v[6:9], 0
	s_waitcnt lgkmcnt(6)
	v_mfma_f32_16x16x32_bf16 v[28:31], v[24:27], v[2:5], 0
	v_mfma_f32_16x16x32_bf16 v[24:27], v[24:27], v[6:9], 0
	s_waitcnt lgkmcnt(5)
	v_mfma_f32_16x16x32_bf16 v[36:39], v[32:35], v[2:5], 0
	v_mfma_f32_16x16x32_bf16 v[32:35], v[32:35], v[6:9], 0
	s_waitcnt lgkmcnt(4)
	v_mfma_f32_16x16x32_bf16 v[44:47], v[40:43], v[2:5], 0
	v_mfma_f32_16x16x32_bf16 v[40:43], v[40:43], v[6:9], 0
	s_waitcnt lgkmcnt(3)
	v_mfma_f32_16x16x32_bf16 v[52:55], v[48:51], v[2:5], 0
	v_mfma_f32_16x16x32_bf16 v[48:51], v[48:51], v[6:9], 0
	s_waitcnt lgkmcnt(2)
	v_mfma_f32_16x16x32_bf16 v[60:63], v[56:59], v[2:5], 0
	v_mfma_f32_16x16x32_bf16 v[56:59], v[56:59], v[6:9], 0
	s_waitcnt lgkmcnt(1)
	v_mfma_f32_16x16x32_bf16 v[68:71], v[64:67], v[2:5], 0
	v_mfma_f32_16x16x32_bf16 v[64:67], v[64:67], v[6:9], 0
	s_waitcnt lgkmcnt(0)
	v_mfma_f32_16x16x32_bf16 v[2:5], v[72:75], v[2:5], 0
	v_mfma_f32_16x16x32_bf16 v[6:9], v[72:75], v[6:9], 0
	ds_read_b128 v[72:75], v10 offset:34880
	ds_read_b128 v[76:79], v10 offset:39232
	ds_read_b128 v[80:83], v11 offset:64
	s_waitcnt lgkmcnt(0)
	v_mfma_f32_16x16x32_bf16 v[20:23], v[80:83], v[72:75], v[20:23]
	v_mfma_f32_16x16x32_bf16 v[14:17], v[80:83], v[76:79], v[14:17]
	ds_read_b128 v[80:83], v11 offset:4416
	s_waitcnt lgkmcnt(0)
	v_mfma_f32_16x16x32_bf16 v[28:31], v[80:83], v[72:75], v[28:31]
	v_mfma_f32_16x16x32_bf16 v[24:27], v[80:83], v[76:79], v[24:27]
	ds_read_b128 v[80:83], v11 offset:8768
	s_waitcnt lgkmcnt(0)
	v_mfma_f32_16x16x32_bf16 v[36:39], v[80:83], v[72:75], v[36:39]
	v_mfma_f32_16x16x32_bf16 v[32:35], v[80:83], v[76:79], v[32:35]
	ds_read_b128 v[80:83], v11 offset:13120
	s_waitcnt lgkmcnt(0)
	v_mfma_f32_16x16x32_bf16 v[44:47], v[80:83], v[72:75], v[44:47]
	v_mfma_f32_16x16x32_bf16 v[40:43], v[80:83], v[76:79], v[40:43]
	ds_read_b128 v[80:83], v11 offset:17472
	s_waitcnt lgkmcnt(0)
	v_mfma_f32_16x16x32_bf16 v[52:55], v[80:83], v[72:75], v[52:55]
	v_mfma_f32_16x16x32_bf16 v[48:51], v[80:83], v[76:79], v[48:51]
	ds_read_b128 v[80:83], v11 offset:21824
	s_waitcnt lgkmcnt(0)
	v_mfma_f32_16x16x32_bf16 v[60:63], v[80:83], v[72:75], v[60:63]
	v_mfma_f32_16x16x32_bf16 v[56:59], v[80:83], v[76:79], v[56:59]
	ds_read_b128 v[80:83], v11 offset:26176
	s_waitcnt lgkmcnt(0)
	v_mfma_f32_16x16x32_bf16 v[68:71], v[80:83], v[72:75], v[68:71]
	v_mfma_f32_16x16x32_bf16 v[64:67], v[80:83], v[76:79], v[64:67]
	ds_read_b128 v[80:83], v11 offset:30528
	s_waitcnt lgkmcnt(0)
	v_mfma_f32_16x16x32_bf16 v[2:5], v[80:83], v[72:75], v[2:5]
	v_mfma_f32_16x16x32_bf16 v[6:9], v[80:83], v[76:79], v[6:9]
	ds_read_b128 v[72:75], v10 offset:34944
	ds_read_b128 v[76:79], v10 offset:39296
	ds_read_b128 v[80:83], v11 offset:128
	s_waitcnt lgkmcnt(0)
	v_mfma_f32_16x16x32_bf16 v[20:23], v[80:83], v[72:75], v[20:23]
	v_mfma_f32_16x16x32_bf16 v[14:17], v[80:83], v[76:79], v[14:17]
	ds_read_b128 v[80:83], v11 offset:4480
	s_waitcnt lgkmcnt(0)
	v_mfma_f32_16x16x32_bf16 v[28:31], v[80:83], v[72:75], v[28:31]
	v_mfma_f32_16x16x32_bf16 v[24:27], v[80:83], v[76:79], v[24:27]
	ds_read_b128 v[80:83], v11 offset:8832
	s_waitcnt lgkmcnt(0)
	v_mfma_f32_16x16x32_bf16 v[36:39], v[80:83], v[72:75], v[36:39]
	v_mfma_f32_16x16x32_bf16 v[32:35], v[80:83], v[76:79], v[32:35]
	ds_read_b128 v[80:83], v11 offset:13184
	s_waitcnt lgkmcnt(0)
	v_mfma_f32_16x16x32_bf16 v[44:47], v[80:83], v[72:75], v[44:47]
	v_mfma_f32_16x16x32_bf16 v[40:43], v[80:83], v[76:79], v[40:43]
	ds_read_b128 v[80:83], v11 offset:17536
	s_waitcnt lgkmcnt(0)
	v_mfma_f32_16x16x32_bf16 v[52:55], v[80:83], v[72:75], v[52:55]
	v_mfma_f32_16x16x32_bf16 v[48:51], v[80:83], v[76:79], v[48:51]
	ds_read_b128 v[80:83], v11 offset:21888
	s_waitcnt lgkmcnt(0)
	v_mfma_f32_16x16x32_bf16 v[60:63], v[80:83], v[72:75], v[60:63]
	v_mfma_f32_16x16x32_bf16 v[56:59], v[80:83], v[76:79], v[56:59]
	ds_read_b128 v[80:83], v11 offset:26240
	s_waitcnt lgkmcnt(0)
	v_mfma_f32_16x16x32_bf16 v[68:71], v[80:83], v[72:75], v[68:71]
	v_mfma_f32_16x16x32_bf16 v[64:67], v[80:83], v[76:79], v[64:67]
	ds_read_b128 v[80:83], v11 offset:30592
	s_waitcnt lgkmcnt(0)
	v_mfma_f32_16x16x32_bf16 v[2:5], v[80:83], v[72:75], v[2:5]
	v_mfma_f32_16x16x32_bf16 v[6:9], v[80:83], v[76:79], v[6:9]
	ds_read_b128 v[72:75], v10 offset:35008
	ds_read_b128 v[76:79], v10 offset:39360
	ds_read_b128 v[80:83], v11 offset:192
	v_ashrrev_i32_e32 v10, 7, v18
	v_add_u32_e32 v10, s6, v10
	s_waitcnt lgkmcnt(0)
	v_mfma_f32_16x16x32_bf16 v[20:23], v[80:83], v[72:75], v[20:23]
	v_and_or_b32 v18, v12, 32, v19
	v_lshl_add_u64 v[12:13], s[4:5], 0, v[0:1]
	v_lshlrev_b32_e32 v0, 9, v18
	v_mfma_f32_16x16x32_bf16 v[14:17], v[80:83], v[76:79], v[14:17]
	ds_read_b128 v[80:83], v11 offset:4544
	s_mov_b64 s[4:5], 0
	s_waitcnt lgkmcnt(0)
	v_mfma_f32_16x16x32_bf16 v[28:31], v[80:83], v[72:75], v[28:31]
	v_mfma_f32_16x16x32_bf16 v[24:27], v[80:83], v[76:79], v[24:27]
	ds_read_b128 v[80:83], v11 offset:8896
	s_waitcnt lgkmcnt(0)
	v_mfma_f32_16x16x32_bf16 v[36:39], v[80:83], v[72:75], v[36:39]
	v_mfma_f32_16x16x32_bf16 v[32:35], v[80:83], v[76:79], v[32:35]
	ds_read_b128 v[80:83], v11 offset:13248
	s_waitcnt lgkmcnt(0)
	v_mfma_f32_16x16x32_bf16 v[44:47], v[80:83], v[72:75], v[44:47]
	v_mfma_f32_16x16x32_bf16 v[40:43], v[80:83], v[76:79], v[40:43]
	ds_read_b128 v[80:83], v11 offset:17600
	s_waitcnt lgkmcnt(0)
	v_mfma_f32_16x16x32_bf16 v[52:55], v[80:83], v[72:75], v[52:55]
	v_mfma_f32_16x16x32_bf16 v[48:51], v[80:83], v[76:79], v[48:51]
	ds_read_b128 v[80:83], v11 offset:21952
	s_waitcnt lgkmcnt(0)
	v_mfma_f32_16x16x32_bf16 v[60:63], v[80:83], v[72:75], v[60:63]
	v_mfma_f32_16x16x32_bf16 v[56:59], v[80:83], v[76:79], v[56:59]
	ds_read_b128 v[80:83], v11 offset:26304
	s_waitcnt lgkmcnt(0)
	v_mfma_f32_16x16x32_bf16 v[68:71], v[80:83], v[72:75], v[68:71]
	v_mfma_f32_16x16x32_bf16 v[64:67], v[80:83], v[76:79], v[64:67]
	ds_read_b128 v[80:83], v11 offset:30656
	v_ashrrev_i32_e32 v11, 31, v10
	v_lshlrev_b64 v[10:11], 15, v[10:11]
	v_lshl_add_u64 v[10:11], v[12:13], 0, v[10:11]
	s_waitcnt lgkmcnt(0)
	v_mfma_f32_16x16x32_bf16 v[2:5], v[80:83], v[72:75], v[2:5]
	v_lshl_add_u64 v[10:11], v[10:11], 0, v[0:1]
	global_store_dwordx4 v[10:11], v[20:23], off
	global_store_dwordx4 v[10:11], v[28:31], off offset:64
	global_store_dwordx4 v[10:11], v[36:39], off offset:128
	global_store_dwordx4 v[10:11], v[44:47], off offset:192
	global_store_dwordx4 v[10:11], v[52:55], off offset:256
	global_store_dwordx4 v[10:11], v[60:63], off offset:320
	global_store_dwordx4 v[10:11], v[68:71], off offset:384
	global_store_dwordx4 v[10:11], v[2:5], off offset:448
	v_mfma_f32_16x16x32_bf16 v[6:9], v[80:83], v[76:79], v[6:9]
	s_nop 0
	v_add_co_u32_e32 v2, vcc, 0x2000, v10
	s_nop 1
	v_addc_co_u32_e32 v3, vcc, 0, v11, vcc
	global_store_dwordx4 v[2:3], v[14:17], off
	global_store_dwordx4 v[2:3], v[24:27], off offset:64
	global_store_dwordx4 v[2:3], v[32:35], off offset:128
	global_store_dwordx4 v[2:3], v[40:43], off offset:192
	global_store_dwordx4 v[2:3], v[48:51], off offset:256
	global_store_dwordx4 v[2:3], v[56:59], off offset:320
	global_store_dwordx4 v[2:3], v[64:67], off offset:384
	global_store_dwordx4 v[2:3], v[6:9], off offset:448

.LBB0_332:
	s_or_b64 exec, exec, s[4:5]
	s_add_i32 s2, s24, 0xffffff80
	v_readlane_b32 s4, v254, 18
	s_add_i32 s4, s2, s4
	s_mul_i32 s5, s6, 0x1400
	v_readlane_b32 s8, v254, 1
	s_mul_hi_u32 s2, s6, 0x1400
	v_readlane_b32 s9, v254, 2
	s_add_u32 s8, s8, s5
	v_ashrrev_i32_e32 v7, 31, v6
	s_addc_u32 s9, s9, s2
	v_lshl_add_u64 v[2:3], v[6:7], 1, s[8:9]
	global_load_ushort v0, v[2:3], off offset:2048
	s_lshl_b64 s[8:9], s[6:7], 5
	v_readlane_b32 s10, v254, 11
	v_readlane_b32 s11, v254, 12
	s_add_u32 s8, s10, s8
	v_ashrrev_i32_e32 v8, 6, v6
	s_addc_u32 s9, s11, s9
	v_readlane_b32 s10, v253, 42
	v_lshl_add_u32 v80, v6, 2, 0
	v_ashrrev_i32_e32 v9, 31, v8
	v_readlane_b32 s11, v253, 43
	v_lshl_add_u64 v[2:3], v[8:9], 2, s[8:9]
	v_readlane_b32 s2, v253, 58
	s_ashr_i32 s5, s4, 31
	v_lshlrev_b64 v[14:15], 13, v[8:9]
	v_add_u32_e32 v10, s2, v8
	v_ashrrev_i32_e32 v11, 31, v10
	s_lshl_b64 s[4:5], s[4:5], 16
	v_lshl_add_u64 v[14:15], v[14:15], 0, s[4:5]
	v_and_b32_e32 v13, 63, v6
	v_lshlrev_b64 v[14:15], 2, v[14:15]
	v_lshl_add_u64 v[18:19], s[12:13], 0, v[14:15]
	v_and_b32_e32 v9, 0xffffffc0, v6
	s_mov_b32 s17, 0
	v_cmp_eq_u32_e64 s[4:5], 0, v13
	s_waitcnt vmcnt(0)
	v_lshlrev_b32_e32 v0, 16, v0
	ds_write_b32 v80, v0 offset:4096
	s_waitcnt lgkmcnt(0)
	s_barrier
	s_load_dwordx2 s[8:9], s[10:11], 0x90
	global_load_dword v81, v[2:3], off
	s_waitcnt lgkmcnt(0)
	v_lshl_add_u64 v[2:3], v[10:11], 2, s[8:9]
	global_load_dword v0, v[2:3], off
	s_load_dwordx2 s[8:9], s[10:11], 0x30
	s_waitcnt lgkmcnt(0)
	v_lshl_add_u64 v[16:17], s[8:9], 0, v[14:15]
	s_mov_b64 s[8:9], -1
	s_waitcnt vmcnt(0)
	v_mul_f32_e32 v0, 0x3fb8aa3b, v0
	v_exp_f32_e32 v0, v0
	s_nop 0
	v_mul_f32_e64 v0, v81, -v0
	v_mul_f32_e32 v0, 0x3fb8aa3b, v0
	v_exp_f32_e32 v12, v0
	v_lshlrev_b32_e32 v0, 1, v6
	v_and_b32_e32 v2, 0xfffffe00, v0
	v_lshlrev_b32_e32 v0, 3, v13
	v_add3_u32 v2, 0, v2, v0
	v_lshl_add_u64 v[14:15], v[16:17], 0, v[0:1]
	v_lshl_add_u64 v[16:17], v[18:19], 0, v[0:1]
	v_and_b32_e32 v0, 64, v243
	v_add_u32_e32 v18, 64, v0
	v_xor_b32_e32 v0, 32, v243
	v_cmp_lt_i32_e32 vcc, v0, v18
	v_xor_b32_e32 v19, 16, v243
	ds_read2st64_b64 v[2:5], v2 offset0:4 offset1:6
	v_cndmask_b32_e32 v0, v243, v0, vcc
	v_cmp_lt_i32_e32 vcc, v19, v18
	v_lshlrev_b32_e32 v0, 2, v0
	v_mov_b32_e32 v13, v12
	v_cndmask_b32_e32 v19, v243, v19, vcc
	v_lshlrev_b32_e32 v82, 2, v19
	v_xor_b32_e32 v19, 8, v243
	v_cmp_lt_i32_e32 vcc, v19, v18
	s_nop 1
	v_cndmask_b32_e32 v19, v243, v19, vcc
	v_lshlrev_b32_e32 v83, 2, v19
	v_xor_b32_e32 v19, 4, v243
	v_cmp_lt_i32_e32 vcc, v19, v18
	s_nop 1
	v_cndmask_b32_e32 v19, v243, v19, vcc
	v_lshlrev_b32_e32 v84, 2, v19
	v_xor_b32_e32 v19, 2, v243
	v_cmp_lt_i32_e32 vcc, v19, v18
	s_nop 1
	v_cndmask_b32_e32 v19, v243, v19, vcc
	v_lshlrev_b32_e32 v85, 2, v19
	v_xor_b32_e32 v19, 1, v243
	v_cmp_lt_i32_e32 vcc, v19, v18
	s_nop 1
	v_cndmask_b32_e32 v18, v243, v19, vcc
	v_lshlrev_b32_e32 v86, 2, v18
	s_branch .LBB0_334
	s_nop 0
.LBB0_333:
	s_or_b64 exec, exec, s[10:11]
	s_xor_b64 s[10:11], s[8:9], -1
	s_mov_b32 s17, 32
	s_mov_b64 s[8:9], 0
	s_and_b64 vcc, exec, s[10:11]
	s_cbranch_vccnz .LBB0_466
